# carry phase: composition chains 3-at-a-time with 16-chunk load batches; fix-up loop 4-deep software pipeline with counted vmcnt
# speedup vs baseline: 1.0205x; 1.0165x over previous
.LBB0_500:
	s_bitcmp1_b32 s61, 2
	s_cselect_b64 s[4:5], -1, 0
	s_xor_b64 s[4:5], s[4:5], -1
	v_cndmask_b32_e64 v2, 0, 1, s[4:5]
	s_lshl_b32 s24, s22, 2
	v_readfirstlane_b32 s4, v2
	s_lshl_b32 s23, s4, 2
	s_and_b32 s4, s61, 0x7c
	s_add_i32 s5, s4, 4
	s_xor_b32 s4, s4, 0x7c
	s_and_b32 s64, s4, 4
	s_and_b32 s65, s4, 0x78
	s_mul_i32 s4, s52, s62
	s_add_i32 s4, s51, s4
	s_and_b32 s63, s5, 0xf8
	s_and_b32 s5, s4, 0x7c
	s_and_b32 s28, s24, 0x7c
	s_ashr_i32 s24, s22, 4
	s_add_i32 s8, s5, 4
	s_or_b32 s33, s5, 3
	s_not_b32 s4, s4
	s_and_b32 s66, s24, -2
	s_cmpk_lg_i32 s28, 0x7c
	s_cselect_b64 s[24:25], -1, 0
	s_addk_i32 s5, 0xff8b
	s_cmp_gt_u32 s5, 6
	s_mul_i32 s26, s28, 0x2800
	s_mul_i32 s40, s28, 0x500
	s_cselect_b64 s[28:29], -1, 0
	s_bitcmp1_b32 s4, 2
	s_cselect_b64 s[30:31], -1, 0
	s_cmp_gt_u32 s33, 6
	s_cselect_b64 s[34:35], -1, 0
	s_bitcmp1_b32 s8, 2
	s_mov_b32 s27, s9
	s_cselect_b64 s[36:37], -1, 0
	s_lshl_b32 s8, s40, 3
	v_mov_b32_e32 v2, v196
	s_mov_b32 s67, s9
	s_waitcnt vmcnt(0)
	s_barrier
	s_lshr_b32 s84, s22, 5
	s_and_b32 s85, s22, 31
	s_lshl_b32 s85, s85, 2
	s_add_u32 s85, s85, 4
	s_sub_u32 s86, s14, 4
	s_subb_u32 s87, s15, 0
	s_mul_i32 s88, s84, 0x294000
	s_add_u32 s86, s86, s88
	s_addc_u32 s87, s87, 0
	v_lshlrev_b32_e32 v52, 3, v196
	v_add_u32_e32 v53, 0x1000, v52
	v_add_u32_e32 v54, 0x2000, v52
	v_cmp_gt_u32_e32 vcc, 0x100, v196
	s_nop 1
	v_cndmask_b32_e32 v54, v53, v54, vcc
	s_mov_b32 s73, 0
.Lcc_dir:
	s_cmp_eq_u32 s73, 0
	s_cbranch_scc0 .Lcc_setup1
	s_mov_b32 s98, s86
	s_mov_b32 s99, s87
	s_mov_b32 s100, 0x2800
	s_mov_b32 s101, 0
	s_mov_b32 s72, s85
	s_mov_b32 s71, 0x1400
	v_lshrrev_b32_e32 v60, 1, v52
	v_lshrrev_b32_e32 v61, 1, v53
	v_lshrrev_b32_e32 v62, 1, v54
	v_mov_b32_e32 v56, 0
	v_mov_b32_e32 v57, 0
	v_mov_b32_e32 v58, 0
	s_branch .Lcc_main
.Lcc_setup1:
	s_add_u32 s98, s86, 0x151800
	s_addc_u32 s99, s87, 0
	s_mov_b32 s100, 0xffffd800
	s_mov_b32 s101, -1
	s_sub_u32 s72, 0x80, s85
	s_mov_b32 s71, 0xffffec00
	v_lshrrev_b32_e32 v60, 1, v52
	v_add_u32_e32 v60, 0x8c00, v60
	v_lshrrev_b32_e32 v61, 1, v53
	v_add_u32_e32 v61, 0x8c00, v61
	v_lshrrev_b32_e32 v62, 1, v54
	v_add_u32_e32 v62, 0x8c00, v62
	v_mov_b32_e32 v56, 0
	v_mov_b32_e32 v57, 0
	v_mov_b32_e32 v58, 0
	global_load_dwordx2 v[64:65], v52, s[98:99]
	global_load_dwordx2 v[66:67], v53, s[98:99]
	global_load_dwordx2 v[68:69], v54, s[98:99]
	s_add_u32 s98, s98, s100
	s_addc_u32 s99, s99, s101
	global_load_dwordx2 v[70:71], v52, s[98:99]
	global_load_dwordx2 v[72:73], v53, s[98:99]
	global_load_dwordx2 v[74:75], v54, s[98:99]
	s_add_u32 s98, s98, s100
	s_addc_u32 s99, s99, s101
	global_load_dwordx2 v[76:77], v52, s[98:99]
	global_load_dwordx2 v[78:79], v53, s[98:99]
	global_load_dwordx2 v[80:81], v54, s[98:99]
	s_add_u32 s98, s98, s100
	s_addc_u32 s99, s99, s101
	global_load_dwordx2 v[82:83], v52, s[98:99]
	global_load_dwordx2 v[84:85], v53, s[98:99]
	global_load_dwordx2 v[86:87], v54, s[98:99]
	s_add_u32 s98, s98, s100
	s_addc_u32 s99, s99, s101
	s_waitcnt vmcnt(0)
	v_fmac_f32_e32 v65, v56, v64
	v_fmac_f32_e32 v67, v57, v66
	v_fmac_f32_e32 v69, v58, v68
	v_fmac_f32_e32 v71, v65, v70
	v_fmac_f32_e32 v73, v67, v72
	v_fmac_f32_e32 v75, v69, v74
	v_fmac_f32_e32 v77, v71, v76
	v_fmac_f32_e32 v79, v73, v78
	v_fmac_f32_e32 v81, v75, v80
	v_fmac_f32_e32 v83, v77, v82
	v_fmac_f32_e32 v85, v79, v84
	v_fmac_f32_e32 v87, v81, v86
	v_mov_b32_e32 v56, v83
	v_mov_b32_e32 v57, v85
	v_mov_b32_e32 v58, v87
	s_add_u32 s98, s86, 0x291800
	s_addc_u32 s99, s87, 0
.Lcc_main:
	s_lshr_b32 s88, s72, 4
	s_cmp_eq_u32 s88, 0
	s_cbranch_scc1 .Lcc_rem
.Lcc_l16:
	global_load_dwordx2 v[64:65], v52, s[98:99]
	global_load_dwordx2 v[66:67], v53, s[98:99]
	global_load_dwordx2 v[68:69], v54, s[98:99]
	s_add_u32 s98, s98, s100
	s_addc_u32 s99, s99, s101
	global_load_dwordx2 v[70:71], v52, s[98:99]
	global_load_dwordx2 v[72:73], v53, s[98:99]
	global_load_dwordx2 v[74:75], v54, s[98:99]
	s_add_u32 s98, s98, s100
	s_addc_u32 s99, s99, s101
	global_load_dwordx2 v[76:77], v52, s[98:99]
	global_load_dwordx2 v[78:79], v53, s[98:99]
	global_load_dwordx2 v[80:81], v54, s[98:99]
	s_add_u32 s98, s98, s100
	s_addc_u32 s99, s99, s101
	global_load_dwordx2 v[82:83], v52, s[98:99]
	global_load_dwordx2 v[84:85], v53, s[98:99]
	global_load_dwordx2 v[86:87], v54, s[98:99]
	s_add_u32 s98, s98, s100
	s_addc_u32 s99, s99, s101
	global_load_dwordx2 v[88:89], v52, s[98:99]
	global_load_dwordx2 v[90:91], v53, s[98:99]
	global_load_dwordx2 v[92:93], v54, s[98:99]
	s_add_u32 s98, s98, s100
	s_addc_u32 s99, s99, s101
	global_load_dwordx2 v[94:95], v52, s[98:99]
	global_load_dwordx2 v[96:97], v53, s[98:99]
	global_load_dwordx2 v[98:99], v54, s[98:99]
	s_add_u32 s98, s98, s100
	s_addc_u32 s99, s99, s101
	global_load_dwordx2 v[100:101], v52, s[98:99]
	global_load_dwordx2 v[102:103], v53, s[98:99]
	global_load_dwordx2 v[104:105], v54, s[98:99]
	s_add_u32 s98, s98, s100
	s_addc_u32 s99, s99, s101
	global_load_dwordx2 v[106:107], v52, s[98:99]
	global_load_dwordx2 v[108:109], v53, s[98:99]
	global_load_dwordx2 v[110:111], v54, s[98:99]
	s_add_u32 s98, s98, s100
	s_addc_u32 s99, s99, s101
	global_load_dwordx2 v[112:113], v52, s[98:99]
	global_load_dwordx2 v[114:115], v53, s[98:99]
	global_load_dwordx2 v[116:117], v54, s[98:99]
	s_add_u32 s98, s98, s100
	s_addc_u32 s99, s99, s101
	global_load_dwordx2 v[118:119], v52, s[98:99]
	global_load_dwordx2 v[120:121], v53, s[98:99]
	global_load_dwordx2 v[122:123], v54, s[98:99]
	s_add_u32 s98, s98, s100
	s_addc_u32 s99, s99, s101
	global_load_dwordx2 v[124:125], v52, s[98:99]
	global_load_dwordx2 v[126:127], v53, s[98:99]
	global_load_dwordx2 v[128:129], v54, s[98:99]
	s_add_u32 s98, s98, s100
	s_addc_u32 s99, s99, s101
	global_load_dwordx2 v[130:131], v52, s[98:99]
	global_load_dwordx2 v[132:133], v53, s[98:99]
	global_load_dwordx2 v[134:135], v54, s[98:99]
	s_add_u32 s98, s98, s100
	s_addc_u32 s99, s99, s101
	global_load_dwordx2 v[136:137], v52, s[98:99]
	global_load_dwordx2 v[138:139], v53, s[98:99]
	global_load_dwordx2 v[140:141], v54, s[98:99]
	s_add_u32 s98, s98, s100
	s_addc_u32 s99, s99, s101
	global_load_dwordx2 v[142:143], v52, s[98:99]
	global_load_dwordx2 v[144:145], v53, s[98:99]
	global_load_dwordx2 v[146:147], v54, s[98:99]
	s_add_u32 s98, s98, s100
	s_addc_u32 s99, s99, s101
	global_load_dwordx2 v[148:149], v52, s[98:99]
	global_load_dwordx2 v[150:151], v53, s[98:99]
	global_load_dwordx2 v[152:153], v54, s[98:99]
	s_add_u32 s98, s98, s100
	s_addc_u32 s99, s99, s101
	global_load_dwordx2 v[154:155], v52, s[98:99]
	global_load_dwordx2 v[156:157], v53, s[98:99]
	global_load_dwordx2 v[158:159], v54, s[98:99]
	s_add_u32 s98, s98, s100
	s_addc_u32 s99, s99, s101
	s_waitcnt vmcnt(0)
	v_fmac_f32_e32 v65, v56, v64
	v_fmac_f32_e32 v67, v57, v66
	v_fmac_f32_e32 v69, v58, v68
	v_fmac_f32_e32 v71, v65, v70
	v_fmac_f32_e32 v73, v67, v72
	v_fmac_f32_e32 v75, v69, v74
	v_fmac_f32_e32 v77, v71, v76
	v_fmac_f32_e32 v79, v73, v78
	v_fmac_f32_e32 v81, v75, v80
	v_fmac_f32_e32 v83, v77, v82
	v_fmac_f32_e32 v85, v79, v84
	v_fmac_f32_e32 v87, v81, v86
	v_fmac_f32_e32 v89, v83, v88
	v_fmac_f32_e32 v91, v85, v90
	v_fmac_f32_e32 v93, v87, v92
	v_fmac_f32_e32 v95, v89, v94
	v_fmac_f32_e32 v97, v91, v96
	v_fmac_f32_e32 v99, v93, v98
	v_fmac_f32_e32 v101, v95, v100
	v_fmac_f32_e32 v103, v97, v102
	v_fmac_f32_e32 v105, v99, v104
	v_fmac_f32_e32 v107, v101, v106
	v_fmac_f32_e32 v109, v103, v108
	v_fmac_f32_e32 v111, v105, v110
	v_fmac_f32_e32 v113, v107, v112
	v_fmac_f32_e32 v115, v109, v114
	v_fmac_f32_e32 v117, v111, v116
	v_fmac_f32_e32 v119, v113, v118
	v_fmac_f32_e32 v121, v115, v120
	v_fmac_f32_e32 v123, v117, v122
	v_fmac_f32_e32 v125, v119, v124
	v_fmac_f32_e32 v127, v121, v126
	v_fmac_f32_e32 v129, v123, v128
	v_fmac_f32_e32 v131, v125, v130
	v_fmac_f32_e32 v133, v127, v132
	v_fmac_f32_e32 v135, v129, v134
	v_fmac_f32_e32 v137, v131, v136
	v_fmac_f32_e32 v139, v133, v138
	v_fmac_f32_e32 v141, v135, v140
	v_fmac_f32_e32 v143, v137, v142
	v_fmac_f32_e32 v145, v139, v144
	v_fmac_f32_e32 v147, v141, v146
	v_fmac_f32_e32 v149, v143, v148
	v_fmac_f32_e32 v151, v145, v150
	v_fmac_f32_e32 v153, v147, v152
	v_fmac_f32_e32 v155, v149, v154
	v_fmac_f32_e32 v157, v151, v156
	v_fmac_f32_e32 v159, v153, v158
	v_mov_b32_e32 v56, v155
	v_mov_b32_e32 v57, v157
	v_mov_b32_e32 v58, v159
	s_sub_u32 s88, s88, 1
	s_cmp_lg_u32 s88, 0
	s_cbranch_scc1 .Lcc_l16
.Lcc_rem:
	s_bfe_u32 s88, s72, 0x20002
	s_cmp_eq_u32 s88, 0
	s_cbranch_scc1 .Lcc_rec
.Lcc_l4:
	global_load_dwordx2 v[64:65], v52, s[98:99]
	global_load_dwordx2 v[66:67], v53, s[98:99]
	global_load_dwordx2 v[68:69], v54, s[98:99]
	s_add_u32 s98, s98, s100
	s_addc_u32 s99, s99, s101
	global_load_dwordx2 v[70:71], v52, s[98:99]
	global_load_dwordx2 v[72:73], v53, s[98:99]
	global_load_dwordx2 v[74:75], v54, s[98:99]
	s_add_u32 s98, s98, s100
	s_addc_u32 s99, s99, s101
	global_load_dwordx2 v[76:77], v52, s[98:99]
	global_load_dwordx2 v[78:79], v53, s[98:99]
	global_load_dwordx2 v[80:81], v54, s[98:99]
	s_add_u32 s98, s98, s100
	s_addc_u32 s99, s99, s101
	global_load_dwordx2 v[82:83], v52, s[98:99]
	global_load_dwordx2 v[84:85], v53, s[98:99]
	global_load_dwordx2 v[86:87], v54, s[98:99]
	s_add_u32 s98, s98, s100
	s_addc_u32 s99, s99, s101
	s_waitcnt vmcnt(0)
	v_fmac_f32_e32 v65, v56, v64
	v_fmac_f32_e32 v67, v57, v66
	v_fmac_f32_e32 v69, v58, v68
	v_fmac_f32_e32 v71, v65, v70
	v_fmac_f32_e32 v73, v67, v72
	v_fmac_f32_e32 v75, v69, v74
	v_fmac_f32_e32 v77, v71, v76
	v_fmac_f32_e32 v79, v73, v78
	v_fmac_f32_e32 v81, v75, v80
	v_fmac_f32_e32 v83, v77, v82
	v_fmac_f32_e32 v85, v79, v84
	v_fmac_f32_e32 v87, v81, v86
	v_mov_b32_e32 v56, v83
	v_mov_b32_e32 v57, v85
	v_mov_b32_e32 v58, v87
	s_sub_u32 s88, s88, 1
	s_cmp_lg_u32 s88, 0
	s_cbranch_scc1 .Lcc_l4
.Lcc_rec:
	global_load_dwordx2 v[64:65], v52, s[98:99]
	global_load_dwordx2 v[66:67], v53, s[98:99]
	global_load_dwordx2 v[68:69], v54, s[98:99]
	s_add_u32 s98, s98, s100
	s_addc_u32 s99, s99, s101
	global_load_dwordx2 v[70:71], v52, s[98:99]
	global_load_dwordx2 v[72:73], v53, s[98:99]
	global_load_dwordx2 v[74:75], v54, s[98:99]
	s_add_u32 s98, s98, s100
	s_addc_u32 s99, s99, s101
	global_load_dwordx2 v[76:77], v52, s[98:99]
	global_load_dwordx2 v[78:79], v53, s[98:99]
	global_load_dwordx2 v[80:81], v54, s[98:99]
	s_add_u32 s98, s98, s100
	s_addc_u32 s99, s99, s101
	global_load_dwordx2 v[82:83], v52, s[98:99]
	global_load_dwordx2 v[84:85], v53, s[98:99]
	global_load_dwordx2 v[86:87], v54, s[98:99]
	s_add_u32 s98, s98, s100
	s_addc_u32 s99, s99, s101
	s_waitcnt vmcnt(0)
	ds_write_b32 v60, v56
	ds_write_b32 v61, v57
	ds_write_b32 v62, v58
	v_fmac_f32_e32 v65, v56, v64
	v_fmac_f32_e32 v67, v57, v66
	v_fmac_f32_e32 v69, v58, v68
	v_add_u32_e32 v60, s71, v60
	v_add_u32_e32 v61, s71, v61
	v_add_u32_e32 v62, s71, v62
	ds_write_b32 v60, v65
	ds_write_b32 v61, v67
	ds_write_b32 v62, v69
	v_fmac_f32_e32 v71, v65, v70
	v_fmac_f32_e32 v73, v67, v72
	v_fmac_f32_e32 v75, v69, v74
	v_add_u32_e32 v60, s71, v60
	v_add_u32_e32 v61, s71, v61
	v_add_u32_e32 v62, s71, v62
	ds_write_b32 v60, v71
	ds_write_b32 v61, v73
	ds_write_b32 v62, v75
	v_fmac_f32_e32 v77, v71, v76
	v_fmac_f32_e32 v79, v73, v78
	v_fmac_f32_e32 v81, v75, v80
	v_add_u32_e32 v60, s71, v60
	v_add_u32_e32 v61, s71, v61
	v_add_u32_e32 v62, s71, v62
	ds_write_b32 v60, v77
	ds_write_b32 v61, v79
	ds_write_b32 v62, v81
	v_fmac_f32_e32 v83, v77, v82
	v_fmac_f32_e32 v85, v79, v84
	v_fmac_f32_e32 v87, v81, v86
	s_add_u32 s73, s73, 1
	s_cmp_lt_u32 s73, 2
	s_cbranch_scc1 .Lcc_dir
.LBB0_518:
	s_ashr_i32 s23, s22, 31
	s_lshl_b64 s[26:27], s[22:23], 8
	s_mov_b64 s[24:25], 0
	v_mov_b32_e32 v4, v196
	s_waitcnt lgkmcnt(0)
	s_barrier
	s_mul_i32 s72, s22, 0x340000
	s_mul_hi_u32 s73, s22, 0x340000
	s_add_u32 s98, s10, s72
	s_addc_u32 s99, s11, s73
	s_cmpk_lt_i32 s22, 0x80
	s_cselect_b32 s100, s39, s49
	s_cselect_b32 s101, s48, s50
	s_mul_i32 s72, s22, 0xa0000
	s_add_u32 s100, s100, s72
	s_addc_u32 s101, s101, 0
	v_mov_b32_e32 v60, v196
	v_mul_u32_u24_e32 v61, 0xcccd, v60
	v_lshrrev_b32_e32 v62, 23, v61
	v_mul_u32_u24_e32 v63, 0xa0, v62
	v_sub_u32_e32 v63, v60, v63
	v_mul_u32_u24_e32 v76, 0x3400, v62
	v_lshl_add_u32 v76, v63, 4, v76
	v_lshrrev_b32_e32 v77, 6, v62
	v_mul_u32_u24_e32 v77, 0x1400, v77
	v_lshl_add_u32 v77, v63, 5, v77
	v_lshlrev_b32_e32 v78, 4, v60
	global_load_dwordx4 v[68:71], v76, s[98:99]
	global_load_dwordx4 v[64:67], v76, s[98:99] offset:2560
	global_load_dwordx4 v[72:75], v78, s[100:101]
	v_add_u32_e32 v60, 0x200, v60
	v_mul_u32_u24_e32 v61, 0xcccd, v60
	v_lshrrev_b32_e32 v62, 23, v61
	v_mul_u32_u24_e32 v63, 0xa0, v62
	v_sub_u32_e32 v63, v60, v63
	v_mul_u32_u24_e32 v92, 0x3400, v62
	v_lshl_add_u32 v92, v63, 4, v92
	v_lshrrev_b32_e32 v93, 6, v62
	v_mul_u32_u24_e32 v93, 0x1400, v93
	v_lshl_add_u32 v93, v63, 5, v93
	v_lshlrev_b32_e32 v94, 4, v60
	global_load_dwordx4 v[84:87], v92, s[98:99]
	global_load_dwordx4 v[80:83], v92, s[98:99] offset:2560
	global_load_dwordx4 v[88:91], v94, s[100:101]
	v_add_u32_e32 v60, 0x200, v60
	v_mul_u32_u24_e32 v61, 0xcccd, v60
	v_lshrrev_b32_e32 v62, 23, v61
	v_mul_u32_u24_e32 v63, 0xa0, v62
	v_sub_u32_e32 v63, v60, v63
	v_mul_u32_u24_e32 v108, 0x3400, v62
	v_lshl_add_u32 v108, v63, 4, v108
	v_lshrrev_b32_e32 v109, 6, v62
	v_mul_u32_u24_e32 v109, 0x1400, v109
	v_lshl_add_u32 v109, v63, 5, v109
	v_lshlrev_b32_e32 v110, 4, v60
	global_load_dwordx4 v[100:103], v108, s[98:99]
	global_load_dwordx4 v[96:99], v108, s[98:99] offset:2560
	global_load_dwordx4 v[104:107], v110, s[100:101]
	v_add_u32_e32 v60, 0x200, v60
	v_mul_u32_u24_e32 v61, 0xcccd, v60
	v_lshrrev_b32_e32 v62, 23, v61
	v_mul_u32_u24_e32 v63, 0xa0, v62
	v_sub_u32_e32 v63, v60, v63
	v_mul_u32_u24_e32 v124, 0x3400, v62
	v_lshl_add_u32 v124, v63, 4, v124
	v_lshrrev_b32_e32 v125, 6, v62
	v_mul_u32_u24_e32 v125, 0x1400, v125
	v_lshl_add_u32 v125, v63, 5, v125
	v_lshlrev_b32_e32 v126, 4, v60
	global_load_dwordx4 v[116:119], v124, s[98:99]
	global_load_dwordx4 v[112:115], v124, s[98:99] offset:2560
	global_load_dwordx4 v[120:123], v126, s[100:101]
	v_add_u32_e32 v60, 0x200, v60
	ds_read_b128 v[128:131], v77
	ds_read_b128 v[132:135], v77 offset:16
	ds_read_b128 v[136:139], v77 offset:20480
	ds_read_b128 v[140:143], v77 offset:20496
	s_waitcnt vmcnt(9)
	s_waitcnt lgkmcnt(0)
	v_lshlrev_b32_e32 v144, 16, v64
	v_and_b32_e32 v145, 0xffff0000, v64
	v_lshlrev_b32_e32 v146, 16, v68
	v_and_b32_e32 v147, 0xffff0000, v68
	v_lshlrev_b32_e32 v148, 16, v72
	v_and_b32_e32 v149, 0xffff0000, v72
	v_pk_mul_f32 v[146:147], v[146:147], v[128:129]
	v_pk_mul_f32 v[148:149], v[148:149], v[136:137]
	v_pk_add_f32 v[146:147], v[146:147], v[144:145]
	v_pk_add_f32 v[146:147], v[146:147], v[148:149]
	v_cvt_pk_bf16_f32 v168, v146, v147
	v_lshlrev_b32_e32 v150, 16, v65
	v_and_b32_e32 v151, 0xffff0000, v65
	v_lshlrev_b32_e32 v152, 16, v69
	v_and_b32_e32 v153, 0xffff0000, v69
	v_lshlrev_b32_e32 v154, 16, v73
	v_and_b32_e32 v155, 0xffff0000, v73
	v_pk_mul_f32 v[152:153], v[152:153], v[130:131]
	v_pk_mul_f32 v[154:155], v[154:155], v[138:139]
	v_pk_add_f32 v[152:153], v[152:153], v[150:151]
	v_pk_add_f32 v[152:153], v[152:153], v[154:155]
	v_cvt_pk_bf16_f32 v169, v152, v153
	v_lshlrev_b32_e32 v156, 16, v66
	v_and_b32_e32 v157, 0xffff0000, v66
	v_lshlrev_b32_e32 v158, 16, v70
	v_and_b32_e32 v159, 0xffff0000, v70
	v_lshlrev_b32_e32 v160, 16, v74
	v_and_b32_e32 v161, 0xffff0000, v74
	v_pk_mul_f32 v[158:159], v[158:159], v[132:133]
	v_pk_mul_f32 v[160:161], v[160:161], v[140:141]
	v_pk_add_f32 v[158:159], v[158:159], v[156:157]
	v_pk_add_f32 v[158:159], v[158:159], v[160:161]
	v_cvt_pk_bf16_f32 v170, v158, v159
	v_lshlrev_b32_e32 v162, 16, v67
	v_and_b32_e32 v163, 0xffff0000, v67
	v_lshlrev_b32_e32 v164, 16, v71
	v_and_b32_e32 v165, 0xffff0000, v71
	v_lshlrev_b32_e32 v166, 16, v75
	v_and_b32_e32 v167, 0xffff0000, v75
	v_pk_mul_f32 v[164:165], v[164:165], v[134:135]
	v_pk_mul_f32 v[166:167], v[166:167], v[142:143]
	v_pk_add_f32 v[164:165], v[164:165], v[162:163]
	v_pk_add_f32 v[164:165], v[164:165], v[166:167]
	v_cvt_pk_bf16_f32 v171, v164, v165
	global_store_dwordx4 v76, v[168:171], s[98:99] offset:2560
	v_mul_u32_u24_e32 v61, 0xcccd, v60
	v_lshrrev_b32_e32 v62, 23, v61
	v_mul_u32_u24_e32 v63, 0xa0, v62
	v_sub_u32_e32 v63, v60, v63
	v_mul_u32_u24_e32 v76, 0x3400, v62
	v_lshl_add_u32 v76, v63, 4, v76
	v_lshrrev_b32_e32 v77, 6, v62
	v_mul_u32_u24_e32 v77, 0x1400, v77
	v_lshl_add_u32 v77, v63, 5, v77
	v_lshlrev_b32_e32 v78, 4, v60
	global_load_dwordx4 v[68:71], v76, s[98:99]
	global_load_dwordx4 v[64:67], v76, s[98:99] offset:2560
	global_load_dwordx4 v[72:75], v78, s[100:101]
	v_add_u32_e32 v60, 0x200, v60
	ds_read_b128 v[128:131], v93
	ds_read_b128 v[132:135], v93 offset:16
	ds_read_b128 v[136:139], v93 offset:20480
	ds_read_b128 v[140:143], v93 offset:20496
	s_waitcnt vmcnt(10)
	s_waitcnt lgkmcnt(0)
	v_lshlrev_b32_e32 v144, 16, v80
	v_and_b32_e32 v145, 0xffff0000, v80
	v_lshlrev_b32_e32 v146, 16, v84
	v_and_b32_e32 v147, 0xffff0000, v84
	v_lshlrev_b32_e32 v148, 16, v88
	v_and_b32_e32 v149, 0xffff0000, v88
	v_pk_mul_f32 v[146:147], v[146:147], v[128:129]
	v_pk_mul_f32 v[148:149], v[148:149], v[136:137]
	v_pk_add_f32 v[146:147], v[146:147], v[144:145]
	v_pk_add_f32 v[146:147], v[146:147], v[148:149]
	v_cvt_pk_bf16_f32 v172, v146, v147
	v_lshlrev_b32_e32 v150, 16, v81
	v_and_b32_e32 v151, 0xffff0000, v81
	v_lshlrev_b32_e32 v152, 16, v85
	v_and_b32_e32 v153, 0xffff0000, v85
	v_lshlrev_b32_e32 v154, 16, v89
	v_and_b32_e32 v155, 0xffff0000, v89
	v_pk_mul_f32 v[152:153], v[152:153], v[130:131]
	v_pk_mul_f32 v[154:155], v[154:155], v[138:139]
	v_pk_add_f32 v[152:153], v[152:153], v[150:151]
	v_pk_add_f32 v[152:153], v[152:153], v[154:155]
	v_cvt_pk_bf16_f32 v173, v152, v153
	v_lshlrev_b32_e32 v156, 16, v82
	v_and_b32_e32 v157, 0xffff0000, v82
	v_lshlrev_b32_e32 v158, 16, v86
	v_and_b32_e32 v159, 0xffff0000, v86
	v_lshlrev_b32_e32 v160, 16, v90
	v_and_b32_e32 v161, 0xffff0000, v90
	v_pk_mul_f32 v[158:159], v[158:159], v[132:133]
	v_pk_mul_f32 v[160:161], v[160:161], v[140:141]
	v_pk_add_f32 v[158:159], v[158:159], v[156:157]
	v_pk_add_f32 v[158:159], v[158:159], v[160:161]
	v_cvt_pk_bf16_f32 v174, v158, v159
	v_lshlrev_b32_e32 v162, 16, v83
	v_and_b32_e32 v163, 0xffff0000, v83
	v_lshlrev_b32_e32 v164, 16, v87
	v_and_b32_e32 v165, 0xffff0000, v87
	v_lshlrev_b32_e32 v166, 16, v91
	v_and_b32_e32 v167, 0xffff0000, v91
	v_pk_mul_f32 v[164:165], v[164:165], v[134:135]
	v_pk_mul_f32 v[166:167], v[166:167], v[142:143]
	v_pk_add_f32 v[164:165], v[164:165], v[162:163]
	v_pk_add_f32 v[164:165], v[164:165], v[166:167]
	v_cvt_pk_bf16_f32 v175, v164, v165
	global_store_dwordx4 v92, v[172:175], s[98:99] offset:2560
	v_mul_u32_u24_e32 v61, 0xcccd, v60
	v_lshrrev_b32_e32 v62, 23, v61
	v_mul_u32_u24_e32 v63, 0xa0, v62
	v_sub_u32_e32 v63, v60, v63
	v_mul_u32_u24_e32 v92, 0x3400, v62
	v_lshl_add_u32 v92, v63, 4, v92
	v_lshrrev_b32_e32 v93, 6, v62
	v_mul_u32_u24_e32 v93, 0x1400, v93
	v_lshl_add_u32 v93, v63, 5, v93
	v_lshlrev_b32_e32 v94, 4, v60
	global_load_dwordx4 v[84:87], v92, s[98:99]
	global_load_dwordx4 v[80:83], v92, s[98:99] offset:2560
	global_load_dwordx4 v[88:91], v94, s[100:101]
	v_add_u32_e32 v60, 0x200, v60
	ds_read_b128 v[128:131], v109
	ds_read_b128 v[132:135], v109 offset:16
	ds_read_b128 v[136:139], v109 offset:20480
	ds_read_b128 v[140:143], v109 offset:20496
	s_waitcnt vmcnt(11)
	s_waitcnt lgkmcnt(0)
	v_lshlrev_b32_e32 v144, 16, v96
	v_and_b32_e32 v145, 0xffff0000, v96
	v_lshlrev_b32_e32 v146, 16, v100
	v_and_b32_e32 v147, 0xffff0000, v100
	v_lshlrev_b32_e32 v148, 16, v104
	v_and_b32_e32 v149, 0xffff0000, v104
	v_pk_mul_f32 v[146:147], v[146:147], v[128:129]
	v_pk_mul_f32 v[148:149], v[148:149], v[136:137]
	v_pk_add_f32 v[146:147], v[146:147], v[144:145]
	v_pk_add_f32 v[146:147], v[146:147], v[148:149]
	v_cvt_pk_bf16_f32 v168, v146, v147
	v_lshlrev_b32_e32 v150, 16, v97
	v_and_b32_e32 v151, 0xffff0000, v97
	v_lshlrev_b32_e32 v152, 16, v101
	v_and_b32_e32 v153, 0xffff0000, v101
	v_lshlrev_b32_e32 v154, 16, v105
	v_and_b32_e32 v155, 0xffff0000, v105
	v_pk_mul_f32 v[152:153], v[152:153], v[130:131]
	v_pk_mul_f32 v[154:155], v[154:155], v[138:139]
	v_pk_add_f32 v[152:153], v[152:153], v[150:151]
	v_pk_add_f32 v[152:153], v[152:153], v[154:155]
	v_cvt_pk_bf16_f32 v169, v152, v153
	v_lshlrev_b32_e32 v156, 16, v98
	v_and_b32_e32 v157, 0xffff0000, v98
	v_lshlrev_b32_e32 v158, 16, v102
	v_and_b32_e32 v159, 0xffff0000, v102
	v_lshlrev_b32_e32 v160, 16, v106
	v_and_b32_e32 v161, 0xffff0000, v106
	v_pk_mul_f32 v[158:159], v[158:159], v[132:133]
	v_pk_mul_f32 v[160:161], v[160:161], v[140:141]
	v_pk_add_f32 v[158:159], v[158:159], v[156:157]
	v_pk_add_f32 v[158:159], v[158:159], v[160:161]
	v_cvt_pk_bf16_f32 v170, v158, v159
	v_lshlrev_b32_e32 v162, 16, v99
	v_and_b32_e32 v163, 0xffff0000, v99
	v_lshlrev_b32_e32 v164, 16, v103
	v_and_b32_e32 v165, 0xffff0000, v103
	v_lshlrev_b32_e32 v166, 16, v107
	v_and_b32_e32 v167, 0xffff0000, v107
	v_pk_mul_f32 v[164:165], v[164:165], v[134:135]
	v_pk_mul_f32 v[166:167], v[166:167], v[142:143]
	v_pk_add_f32 v[164:165], v[164:165], v[162:163]
	v_pk_add_f32 v[164:165], v[164:165], v[166:167]
	v_cvt_pk_bf16_f32 v171, v164, v165
	global_store_dwordx4 v108, v[168:171], s[98:99] offset:2560
	v_mul_u32_u24_e32 v61, 0xcccd, v60
	v_lshrrev_b32_e32 v62, 23, v61
	v_mul_u32_u24_e32 v63, 0xa0, v62
	v_sub_u32_e32 v63, v60, v63
	v_mul_u32_u24_e32 v108, 0x3400, v62
	v_lshl_add_u32 v108, v63, 4, v108
	v_lshrrev_b32_e32 v109, 6, v62
	v_mul_u32_u24_e32 v109, 0x1400, v109
	v_lshl_add_u32 v109, v63, 5, v109
	v_lshlrev_b32_e32 v110, 4, v60
	global_load_dwordx4 v[100:103], v108, s[98:99]
	global_load_dwordx4 v[96:99], v108, s[98:99] offset:2560
	global_load_dwordx4 v[104:107], v110, s[100:101]
	v_add_u32_e32 v60, 0x200, v60
	ds_read_b128 v[128:131], v125
	ds_read_b128 v[132:135], v125 offset:16
	ds_read_b128 v[136:139], v125 offset:20480
	ds_read_b128 v[140:143], v125 offset:20496
	s_waitcnt vmcnt(12)
	s_waitcnt lgkmcnt(0)
	v_lshlrev_b32_e32 v144, 16, v112
	v_and_b32_e32 v145, 0xffff0000, v112
	v_lshlrev_b32_e32 v146, 16, v116
	v_and_b32_e32 v147, 0xffff0000, v116
	v_lshlrev_b32_e32 v148, 16, v120
	v_and_b32_e32 v149, 0xffff0000, v120
	v_pk_mul_f32 v[146:147], v[146:147], v[128:129]
	v_pk_mul_f32 v[148:149], v[148:149], v[136:137]
	v_pk_add_f32 v[146:147], v[146:147], v[144:145]
	v_pk_add_f32 v[146:147], v[146:147], v[148:149]
	v_cvt_pk_bf16_f32 v172, v146, v147
	v_lshlrev_b32_e32 v150, 16, v113
	v_and_b32_e32 v151, 0xffff0000, v113
	v_lshlrev_b32_e32 v152, 16, v117
	v_and_b32_e32 v153, 0xffff0000, v117
	v_lshlrev_b32_e32 v154, 16, v121
	v_and_b32_e32 v155, 0xffff0000, v121
	v_pk_mul_f32 v[152:153], v[152:153], v[130:131]
	v_pk_mul_f32 v[154:155], v[154:155], v[138:139]
	v_pk_add_f32 v[152:153], v[152:153], v[150:151]
	v_pk_add_f32 v[152:153], v[152:153], v[154:155]
	v_cvt_pk_bf16_f32 v173, v152, v153
	v_lshlrev_b32_e32 v156, 16, v114
	v_and_b32_e32 v157, 0xffff0000, v114
	v_lshlrev_b32_e32 v158, 16, v118
	v_and_b32_e32 v159, 0xffff0000, v118
	v_lshlrev_b32_e32 v160, 16, v122
	v_and_b32_e32 v161, 0xffff0000, v122
	v_pk_mul_f32 v[158:159], v[158:159], v[132:133]
	v_pk_mul_f32 v[160:161], v[160:161], v[140:141]
	v_pk_add_f32 v[158:159], v[158:159], v[156:157]
	v_pk_add_f32 v[158:159], v[158:159], v[160:161]
	v_cvt_pk_bf16_f32 v174, v158, v159
	v_lshlrev_b32_e32 v162, 16, v115
	v_and_b32_e32 v163, 0xffff0000, v115
	v_lshlrev_b32_e32 v164, 16, v119
	v_and_b32_e32 v165, 0xffff0000, v119
	v_lshlrev_b32_e32 v166, 16, v123
	v_and_b32_e32 v167, 0xffff0000, v123
	v_pk_mul_f32 v[164:165], v[164:165], v[134:135]
	v_pk_mul_f32 v[166:167], v[166:167], v[142:143]
	v_pk_add_f32 v[164:165], v[164:165], v[162:163]
	v_pk_add_f32 v[164:165], v[164:165], v[166:167]
	v_cvt_pk_bf16_f32 v175, v164, v165
	global_store_dwordx4 v124, v[172:175], s[98:99] offset:2560
	v_mul_u32_u24_e32 v61, 0xcccd, v60
	v_lshrrev_b32_e32 v62, 23, v61
	v_mul_u32_u24_e32 v63, 0xa0, v62
	v_sub_u32_e32 v63, v60, v63
	v_mul_u32_u24_e32 v124, 0x3400, v62
	v_lshl_add_u32 v124, v63, 4, v124
	v_lshrrev_b32_e32 v125, 6, v62
	v_mul_u32_u24_e32 v125, 0x1400, v125
	v_lshl_add_u32 v125, v63, 5, v125
	v_lshlrev_b32_e32 v126, 4, v60
	global_load_dwordx4 v[116:119], v124, s[98:99]
	global_load_dwordx4 v[112:115], v124, s[98:99] offset:2560
	global_load_dwordx4 v[120:123], v126, s[100:101]
	v_add_u32_e32 v60, 0x200, v60
	s_mov_b32 s71, 18
.Lcf_loop:
	ds_read_b128 v[128:131], v77
	ds_read_b128 v[132:135], v77 offset:16
	ds_read_b128 v[136:139], v77 offset:20480
	ds_read_b128 v[140:143], v77 offset:20496
	s_waitcnt vmcnt(12)
	s_waitcnt lgkmcnt(0)
	v_lshlrev_b32_e32 v144, 16, v64
	v_and_b32_e32 v145, 0xffff0000, v64
	v_lshlrev_b32_e32 v146, 16, v68
	v_and_b32_e32 v147, 0xffff0000, v68
	v_lshlrev_b32_e32 v148, 16, v72
	v_and_b32_e32 v149, 0xffff0000, v72
	v_pk_mul_f32 v[146:147], v[146:147], v[128:129]
	v_pk_mul_f32 v[148:149], v[148:149], v[136:137]
	v_pk_add_f32 v[146:147], v[146:147], v[144:145]
	v_pk_add_f32 v[146:147], v[146:147], v[148:149]
	v_cvt_pk_bf16_f32 v168, v146, v147
	v_lshlrev_b32_e32 v150, 16, v65
	v_and_b32_e32 v151, 0xffff0000, v65
	v_lshlrev_b32_e32 v152, 16, v69
	v_and_b32_e32 v153, 0xffff0000, v69
	v_lshlrev_b32_e32 v154, 16, v73
	v_and_b32_e32 v155, 0xffff0000, v73
	v_pk_mul_f32 v[152:153], v[152:153], v[130:131]
	v_pk_mul_f32 v[154:155], v[154:155], v[138:139]
	v_pk_add_f32 v[152:153], v[152:153], v[150:151]
	v_pk_add_f32 v[152:153], v[152:153], v[154:155]
	v_cvt_pk_bf16_f32 v169, v152, v153
	v_lshlrev_b32_e32 v156, 16, v66
	v_and_b32_e32 v157, 0xffff0000, v66
	v_lshlrev_b32_e32 v158, 16, v70
	v_and_b32_e32 v159, 0xffff0000, v70
	v_lshlrev_b32_e32 v160, 16, v74
	v_and_b32_e32 v161, 0xffff0000, v74
	v_pk_mul_f32 v[158:159], v[158:159], v[132:133]
	v_pk_mul_f32 v[160:161], v[160:161], v[140:141]
	v_pk_add_f32 v[158:159], v[158:159], v[156:157]
	v_pk_add_f32 v[158:159], v[158:159], v[160:161]
	v_cvt_pk_bf16_f32 v170, v158, v159
	v_lshlrev_b32_e32 v162, 16, v67
	v_and_b32_e32 v163, 0xffff0000, v67
	v_lshlrev_b32_e32 v164, 16, v71
	v_and_b32_e32 v165, 0xffff0000, v71
	v_lshlrev_b32_e32 v166, 16, v75
	v_and_b32_e32 v167, 0xffff0000, v75
	v_pk_mul_f32 v[164:165], v[164:165], v[134:135]
	v_pk_mul_f32 v[166:167], v[166:167], v[142:143]
	v_pk_add_f32 v[164:165], v[164:165], v[162:163]
	v_pk_add_f32 v[164:165], v[164:165], v[166:167]
	v_cvt_pk_bf16_f32 v171, v164, v165
	global_store_dwordx4 v76, v[168:171], s[98:99] offset:2560
	v_mul_u32_u24_e32 v61, 0xcccd, v60
	v_lshrrev_b32_e32 v62, 23, v61
	v_mul_u32_u24_e32 v63, 0xa0, v62
	v_sub_u32_e32 v63, v60, v63
	v_mul_u32_u24_e32 v76, 0x3400, v62
	v_lshl_add_u32 v76, v63, 4, v76
	v_lshrrev_b32_e32 v77, 6, v62
	v_mul_u32_u24_e32 v77, 0x1400, v77
	v_lshl_add_u32 v77, v63, 5, v77
	v_lshlrev_b32_e32 v78, 4, v60
	global_load_dwordx4 v[68:71], v76, s[98:99]
	global_load_dwordx4 v[64:67], v76, s[98:99] offset:2560
	global_load_dwordx4 v[72:75], v78, s[100:101]
	v_add_u32_e32 v60, 0x200, v60
	ds_read_b128 v[128:131], v93
	ds_read_b128 v[132:135], v93 offset:16
	ds_read_b128 v[136:139], v93 offset:20480
	ds_read_b128 v[140:143], v93 offset:20496
	s_waitcnt vmcnt(12)
	s_waitcnt lgkmcnt(0)
	v_lshlrev_b32_e32 v144, 16, v80
	v_and_b32_e32 v145, 0xffff0000, v80
	v_lshlrev_b32_e32 v146, 16, v84
	v_and_b32_e32 v147, 0xffff0000, v84
	v_lshlrev_b32_e32 v148, 16, v88
	v_and_b32_e32 v149, 0xffff0000, v88
	v_pk_mul_f32 v[146:147], v[146:147], v[128:129]
	v_pk_mul_f32 v[148:149], v[148:149], v[136:137]
	v_pk_add_f32 v[146:147], v[146:147], v[144:145]
	v_pk_add_f32 v[146:147], v[146:147], v[148:149]
	v_cvt_pk_bf16_f32 v172, v146, v147
	v_lshlrev_b32_e32 v150, 16, v81
	v_and_b32_e32 v151, 0xffff0000, v81
	v_lshlrev_b32_e32 v152, 16, v85
	v_and_b32_e32 v153, 0xffff0000, v85
	v_lshlrev_b32_e32 v154, 16, v89
	v_and_b32_e32 v155, 0xffff0000, v89
	v_pk_mul_f32 v[152:153], v[152:153], v[130:131]
	v_pk_mul_f32 v[154:155], v[154:155], v[138:139]
	v_pk_add_f32 v[152:153], v[152:153], v[150:151]
	v_pk_add_f32 v[152:153], v[152:153], v[154:155]
	v_cvt_pk_bf16_f32 v173, v152, v153
	v_lshlrev_b32_e32 v156, 16, v82
	v_and_b32_e32 v157, 0xffff0000, v82
	v_lshlrev_b32_e32 v158, 16, v86
	v_and_b32_e32 v159, 0xffff0000, v86
	v_lshlrev_b32_e32 v160, 16, v90
	v_and_b32_e32 v161, 0xffff0000, v90
	v_pk_mul_f32 v[158:159], v[158:159], v[132:133]
	v_pk_mul_f32 v[160:161], v[160:161], v[140:141]
	v_pk_add_f32 v[158:159], v[158:159], v[156:157]
	v_pk_add_f32 v[158:159], v[158:159], v[160:161]
	v_cvt_pk_bf16_f32 v174, v158, v159
	v_lshlrev_b32_e32 v162, 16, v83
	v_and_b32_e32 v163, 0xffff0000, v83
	v_lshlrev_b32_e32 v164, 16, v87
	v_and_b32_e32 v165, 0xffff0000, v87
	v_lshlrev_b32_e32 v166, 16, v91
	v_and_b32_e32 v167, 0xffff0000, v91
	v_pk_mul_f32 v[164:165], v[164:165], v[134:135]
	v_pk_mul_f32 v[166:167], v[166:167], v[142:143]
	v_pk_add_f32 v[164:165], v[164:165], v[162:163]
	v_pk_add_f32 v[164:165], v[164:165], v[166:167]
	v_cvt_pk_bf16_f32 v175, v164, v165
	global_store_dwordx4 v92, v[172:175], s[98:99] offset:2560
	v_mul_u32_u24_e32 v61, 0xcccd, v60
	v_lshrrev_b32_e32 v62, 23, v61
	v_mul_u32_u24_e32 v63, 0xa0, v62
	v_sub_u32_e32 v63, v60, v63
	v_mul_u32_u24_e32 v92, 0x3400, v62
	v_lshl_add_u32 v92, v63, 4, v92
	v_lshrrev_b32_e32 v93, 6, v62
	v_mul_u32_u24_e32 v93, 0x1400, v93
	v_lshl_add_u32 v93, v63, 5, v93
	v_lshlrev_b32_e32 v94, 4, v60
	global_load_dwordx4 v[84:87], v92, s[98:99]
	global_load_dwordx4 v[80:83], v92, s[98:99] offset:2560
	global_load_dwordx4 v[88:91], v94, s[100:101]
	v_add_u32_e32 v60, 0x200, v60
	ds_read_b128 v[128:131], v109
	ds_read_b128 v[132:135], v109 offset:16
	ds_read_b128 v[136:139], v109 offset:20480
	ds_read_b128 v[140:143], v109 offset:20496
	s_waitcnt vmcnt(12)
	s_waitcnt lgkmcnt(0)
	v_lshlrev_b32_e32 v144, 16, v96
	v_and_b32_e32 v145, 0xffff0000, v96
	v_lshlrev_b32_e32 v146, 16, v100
	v_and_b32_e32 v147, 0xffff0000, v100
	v_lshlrev_b32_e32 v148, 16, v104
	v_and_b32_e32 v149, 0xffff0000, v104
	v_pk_mul_f32 v[146:147], v[146:147], v[128:129]
	v_pk_mul_f32 v[148:149], v[148:149], v[136:137]
	v_pk_add_f32 v[146:147], v[146:147], v[144:145]
	v_pk_add_f32 v[146:147], v[146:147], v[148:149]
	v_cvt_pk_bf16_f32 v168, v146, v147
	v_lshlrev_b32_e32 v150, 16, v97
	v_and_b32_e32 v151, 0xffff0000, v97
	v_lshlrev_b32_e32 v152, 16, v101
	v_and_b32_e32 v153, 0xffff0000, v101
	v_lshlrev_b32_e32 v154, 16, v105
	v_and_b32_e32 v155, 0xffff0000, v105
	v_pk_mul_f32 v[152:153], v[152:153], v[130:131]
	v_pk_mul_f32 v[154:155], v[154:155], v[138:139]
	v_pk_add_f32 v[152:153], v[152:153], v[150:151]
	v_pk_add_f32 v[152:153], v[152:153], v[154:155]
	v_cvt_pk_bf16_f32 v169, v152, v153
	v_lshlrev_b32_e32 v156, 16, v98
	v_and_b32_e32 v157, 0xffff0000, v98
	v_lshlrev_b32_e32 v158, 16, v102
	v_and_b32_e32 v159, 0xffff0000, v102
	v_lshlrev_b32_e32 v160, 16, v106
	v_and_b32_e32 v161, 0xffff0000, v106
	v_pk_mul_f32 v[158:159], v[158:159], v[132:133]
	v_pk_mul_f32 v[160:161], v[160:161], v[140:141]
	v_pk_add_f32 v[158:159], v[158:159], v[156:157]
	v_pk_add_f32 v[158:159], v[158:159], v[160:161]
	v_cvt_pk_bf16_f32 v170, v158, v159
	v_lshlrev_b32_e32 v162, 16, v99
	v_and_b32_e32 v163, 0xffff0000, v99
	v_lshlrev_b32_e32 v164, 16, v103
	v_and_b32_e32 v165, 0xffff0000, v103
	v_lshlrev_b32_e32 v166, 16, v107
	v_and_b32_e32 v167, 0xffff0000, v107
	v_pk_mul_f32 v[164:165], v[164:165], v[134:135]
	v_pk_mul_f32 v[166:167], v[166:167], v[142:143]
	v_pk_add_f32 v[164:165], v[164:165], v[162:163]
	v_pk_add_f32 v[164:165], v[164:165], v[166:167]
	v_cvt_pk_bf16_f32 v171, v164, v165
	global_store_dwordx4 v108, v[168:171], s[98:99] offset:2560
	v_mul_u32_u24_e32 v61, 0xcccd, v60
	v_lshrrev_b32_e32 v62, 23, v61
	v_mul_u32_u24_e32 v63, 0xa0, v62
	v_sub_u32_e32 v63, v60, v63
	v_mul_u32_u24_e32 v108, 0x3400, v62
	v_lshl_add_u32 v108, v63, 4, v108
	v_lshrrev_b32_e32 v109, 6, v62
	v_mul_u32_u24_e32 v109, 0x1400, v109
	v_lshl_add_u32 v109, v63, 5, v109
	v_lshlrev_b32_e32 v110, 4, v60
	global_load_dwordx4 v[100:103], v108, s[98:99]
	global_load_dwordx4 v[96:99], v108, s[98:99] offset:2560
	global_load_dwordx4 v[104:107], v110, s[100:101]
	v_add_u32_e32 v60, 0x200, v60
	ds_read_b128 v[128:131], v125
	ds_read_b128 v[132:135], v125 offset:16
	ds_read_b128 v[136:139], v125 offset:20480
	ds_read_b128 v[140:143], v125 offset:20496
	s_waitcnt vmcnt(12)
	s_waitcnt lgkmcnt(0)
	v_lshlrev_b32_e32 v144, 16, v112
	v_and_b32_e32 v145, 0xffff0000, v112
	v_lshlrev_b32_e32 v146, 16, v116
	v_and_b32_e32 v147, 0xffff0000, v116
	v_lshlrev_b32_e32 v148, 16, v120
	v_and_b32_e32 v149, 0xffff0000, v120
	v_pk_mul_f32 v[146:147], v[146:147], v[128:129]
	v_pk_mul_f32 v[148:149], v[148:149], v[136:137]
	v_pk_add_f32 v[146:147], v[146:147], v[144:145]
	v_pk_add_f32 v[146:147], v[146:147], v[148:149]
	v_cvt_pk_bf16_f32 v172, v146, v147
	v_lshlrev_b32_e32 v150, 16, v113
	v_and_b32_e32 v151, 0xffff0000, v113
	v_lshlrev_b32_e32 v152, 16, v117
	v_and_b32_e32 v153, 0xffff0000, v117
	v_lshlrev_b32_e32 v154, 16, v121
	v_and_b32_e32 v155, 0xffff0000, v121
	v_pk_mul_f32 v[152:153], v[152:153], v[130:131]
	v_pk_mul_f32 v[154:155], v[154:155], v[138:139]
	v_pk_add_f32 v[152:153], v[152:153], v[150:151]
	v_pk_add_f32 v[152:153], v[152:153], v[154:155]
	v_cvt_pk_bf16_f32 v173, v152, v153
	v_lshlrev_b32_e32 v156, 16, v114
	v_and_b32_e32 v157, 0xffff0000, v114
	v_lshlrev_b32_e32 v158, 16, v118
	v_and_b32_e32 v159, 0xffff0000, v118
	v_lshlrev_b32_e32 v160, 16, v122
	v_and_b32_e32 v161, 0xffff0000, v122
	v_pk_mul_f32 v[158:159], v[158:159], v[132:133]
	v_pk_mul_f32 v[160:161], v[160:161], v[140:141]
	v_pk_add_f32 v[158:159], v[158:159], v[156:157]
	v_pk_add_f32 v[158:159], v[158:159], v[160:161]
	v_cvt_pk_bf16_f32 v174, v158, v159
	v_lshlrev_b32_e32 v162, 16, v115
	v_and_b32_e32 v163, 0xffff0000, v115
	v_lshlrev_b32_e32 v164, 16, v119
	v_and_b32_e32 v165, 0xffff0000, v119
	v_lshlrev_b32_e32 v166, 16, v123
	v_and_b32_e32 v167, 0xffff0000, v123
	v_pk_mul_f32 v[164:165], v[164:165], v[134:135]
	v_pk_mul_f32 v[166:167], v[166:167], v[142:143]
	v_pk_add_f32 v[164:165], v[164:165], v[162:163]
	v_pk_add_f32 v[164:165], v[164:165], v[166:167]
	v_cvt_pk_bf16_f32 v175, v164, v165
	global_store_dwordx4 v124, v[172:175], s[98:99] offset:2560
	v_mul_u32_u24_e32 v61, 0xcccd, v60
	v_lshrrev_b32_e32 v62, 23, v61
	v_mul_u32_u24_e32 v63, 0xa0, v62
	v_sub_u32_e32 v63, v60, v63
	v_mul_u32_u24_e32 v124, 0x3400, v62
	v_lshl_add_u32 v124, v63, 4, v124
	v_lshrrev_b32_e32 v125, 6, v62
	v_mul_u32_u24_e32 v125, 0x1400, v125
	v_lshl_add_u32 v125, v63, 5, v125
	v_lshlrev_b32_e32 v126, 4, v60
	global_load_dwordx4 v[116:119], v124, s[98:99]
	global_load_dwordx4 v[112:115], v124, s[98:99] offset:2560
	global_load_dwordx4 v[120:123], v126, s[100:101]
	v_add_u32_e32 v60, 0x200, v60
	s_sub_u32 s71, s71, 1
	s_cmp_lg_u32 s71, 0
	s_cbranch_scc1 .Lcf_loop
	ds_read_b128 v[128:131], v77
	ds_read_b128 v[132:135], v77 offset:16
	ds_read_b128 v[136:139], v77 offset:20480
	ds_read_b128 v[140:143], v77 offset:20496
	s_waitcnt vmcnt(12)
	s_waitcnt lgkmcnt(0)
	v_lshlrev_b32_e32 v144, 16, v64
	v_and_b32_e32 v145, 0xffff0000, v64
	v_lshlrev_b32_e32 v146, 16, v68
	v_and_b32_e32 v147, 0xffff0000, v68
	v_lshlrev_b32_e32 v148, 16, v72
	v_and_b32_e32 v149, 0xffff0000, v72
	v_pk_mul_f32 v[146:147], v[146:147], v[128:129]
	v_pk_mul_f32 v[148:149], v[148:149], v[136:137]
	v_pk_add_f32 v[146:147], v[146:147], v[144:145]
	v_pk_add_f32 v[146:147], v[146:147], v[148:149]
	v_cvt_pk_bf16_f32 v168, v146, v147
	v_lshlrev_b32_e32 v150, 16, v65
	v_and_b32_e32 v151, 0xffff0000, v65
	v_lshlrev_b32_e32 v152, 16, v69
	v_and_b32_e32 v153, 0xffff0000, v69
	v_lshlrev_b32_e32 v154, 16, v73
	v_and_b32_e32 v155, 0xffff0000, v73
	v_pk_mul_f32 v[152:153], v[152:153], v[130:131]
	v_pk_mul_f32 v[154:155], v[154:155], v[138:139]
	v_pk_add_f32 v[152:153], v[152:153], v[150:151]
	v_pk_add_f32 v[152:153], v[152:153], v[154:155]
	v_cvt_pk_bf16_f32 v169, v152, v153
	v_lshlrev_b32_e32 v156, 16, v66
	v_and_b32_e32 v157, 0xffff0000, v66
	v_lshlrev_b32_e32 v158, 16, v70
	v_and_b32_e32 v159, 0xffff0000, v70
	v_lshlrev_b32_e32 v160, 16, v74
	v_and_b32_e32 v161, 0xffff0000, v74
	v_pk_mul_f32 v[158:159], v[158:159], v[132:133]
	v_pk_mul_f32 v[160:161], v[160:161], v[140:141]
	v_pk_add_f32 v[158:159], v[158:159], v[156:157]
	v_pk_add_f32 v[158:159], v[158:159], v[160:161]
	v_cvt_pk_bf16_f32 v170, v158, v159
	v_lshlrev_b32_e32 v162, 16, v67
	v_and_b32_e32 v163, 0xffff0000, v67
	v_lshlrev_b32_e32 v164, 16, v71
	v_and_b32_e32 v165, 0xffff0000, v71
	v_lshlrev_b32_e32 v166, 16, v75
	v_and_b32_e32 v167, 0xffff0000, v75
	v_pk_mul_f32 v[164:165], v[164:165], v[134:135]
	v_pk_mul_f32 v[166:167], v[166:167], v[142:143]
	v_pk_add_f32 v[164:165], v[164:165], v[162:163]
	v_pk_add_f32 v[164:165], v[164:165], v[166:167]
	v_cvt_pk_bf16_f32 v171, v164, v165
	global_store_dwordx4 v76, v[168:171], s[98:99] offset:2560
	ds_read_b128 v[128:131], v93
	ds_read_b128 v[132:135], v93 offset:16
	ds_read_b128 v[136:139], v93 offset:20480
	ds_read_b128 v[140:143], v93 offset:20496
	s_waitcnt vmcnt(9)
	s_waitcnt lgkmcnt(0)
	v_lshlrev_b32_e32 v144, 16, v80
	v_and_b32_e32 v145, 0xffff0000, v80
	v_lshlrev_b32_e32 v146, 16, v84
	v_and_b32_e32 v147, 0xffff0000, v84
	v_lshlrev_b32_e32 v148, 16, v88
	v_and_b32_e32 v149, 0xffff0000, v88
	v_pk_mul_f32 v[146:147], v[146:147], v[128:129]
	v_pk_mul_f32 v[148:149], v[148:149], v[136:137]
	v_pk_add_f32 v[146:147], v[146:147], v[144:145]
	v_pk_add_f32 v[146:147], v[146:147], v[148:149]
	v_cvt_pk_bf16_f32 v172, v146, v147
	v_lshlrev_b32_e32 v150, 16, v81
	v_and_b32_e32 v151, 0xffff0000, v81
	v_lshlrev_b32_e32 v152, 16, v85
	v_and_b32_e32 v153, 0xffff0000, v85
	v_lshlrev_b32_e32 v154, 16, v89
	v_and_b32_e32 v155, 0xffff0000, v89
	v_pk_mul_f32 v[152:153], v[152:153], v[130:131]
	v_pk_mul_f32 v[154:155], v[154:155], v[138:139]
	v_pk_add_f32 v[152:153], v[152:153], v[150:151]
	v_pk_add_f32 v[152:153], v[152:153], v[154:155]
	v_cvt_pk_bf16_f32 v173, v152, v153
	v_lshlrev_b32_e32 v156, 16, v82
	v_and_b32_e32 v157, 0xffff0000, v82
	v_lshlrev_b32_e32 v158, 16, v86
	v_and_b32_e32 v159, 0xffff0000, v86
	v_lshlrev_b32_e32 v160, 16, v90
	v_and_b32_e32 v161, 0xffff0000, v90
	v_pk_mul_f32 v[158:159], v[158:159], v[132:133]
	v_pk_mul_f32 v[160:161], v[160:161], v[140:141]
	v_pk_add_f32 v[158:159], v[158:159], v[156:157]
	v_pk_add_f32 v[158:159], v[158:159], v[160:161]
	v_cvt_pk_bf16_f32 v174, v158, v159
	v_lshlrev_b32_e32 v162, 16, v83
	v_and_b32_e32 v163, 0xffff0000, v83
	v_lshlrev_b32_e32 v164, 16, v87
	v_and_b32_e32 v165, 0xffff0000, v87
	v_lshlrev_b32_e32 v166, 16, v91
	v_and_b32_e32 v167, 0xffff0000, v91
	v_pk_mul_f32 v[164:165], v[164:165], v[134:135]
	v_pk_mul_f32 v[166:167], v[166:167], v[142:143]
	v_pk_add_f32 v[164:165], v[164:165], v[162:163]
	v_pk_add_f32 v[164:165], v[164:165], v[166:167]
	v_cvt_pk_bf16_f32 v175, v164, v165
	global_store_dwordx4 v92, v[172:175], s[98:99] offset:2560
	ds_read_b128 v[128:131], v109
	ds_read_b128 v[132:135], v109 offset:16
	ds_read_b128 v[136:139], v109 offset:20480
	ds_read_b128 v[140:143], v109 offset:20496
	s_waitcnt vmcnt(6)
	s_waitcnt lgkmcnt(0)
	v_lshlrev_b32_e32 v144, 16, v96
	v_and_b32_e32 v145, 0xffff0000, v96
	v_lshlrev_b32_e32 v146, 16, v100
	v_and_b32_e32 v147, 0xffff0000, v100
	v_lshlrev_b32_e32 v148, 16, v104
	v_and_b32_e32 v149, 0xffff0000, v104
	v_pk_mul_f32 v[146:147], v[146:147], v[128:129]
	v_pk_mul_f32 v[148:149], v[148:149], v[136:137]
	v_pk_add_f32 v[146:147], v[146:147], v[144:145]
	v_pk_add_f32 v[146:147], v[146:147], v[148:149]
	v_cvt_pk_bf16_f32 v168, v146, v147
	v_lshlrev_b32_e32 v150, 16, v97
	v_and_b32_e32 v151, 0xffff0000, v97
	v_lshlrev_b32_e32 v152, 16, v101
	v_and_b32_e32 v153, 0xffff0000, v101
	v_lshlrev_b32_e32 v154, 16, v105
	v_and_b32_e32 v155, 0xffff0000, v105
	v_pk_mul_f32 v[152:153], v[152:153], v[130:131]
	v_pk_mul_f32 v[154:155], v[154:155], v[138:139]
	v_pk_add_f32 v[152:153], v[152:153], v[150:151]
	v_pk_add_f32 v[152:153], v[152:153], v[154:155]
	v_cvt_pk_bf16_f32 v169, v152, v153
	v_lshlrev_b32_e32 v156, 16, v98
	v_and_b32_e32 v157, 0xffff0000, v98
	v_lshlrev_b32_e32 v158, 16, v102
	v_and_b32_e32 v159, 0xffff0000, v102
	v_lshlrev_b32_e32 v160, 16, v106
	v_and_b32_e32 v161, 0xffff0000, v106
	v_pk_mul_f32 v[158:159], v[158:159], v[132:133]
	v_pk_mul_f32 v[160:161], v[160:161], v[140:141]
	v_pk_add_f32 v[158:159], v[158:159], v[156:157]
	v_pk_add_f32 v[158:159], v[158:159], v[160:161]
	v_cvt_pk_bf16_f32 v170, v158, v159
	v_lshlrev_b32_e32 v162, 16, v99
	v_and_b32_e32 v163, 0xffff0000, v99
	v_lshlrev_b32_e32 v164, 16, v103
	v_and_b32_e32 v165, 0xffff0000, v103
	v_lshlrev_b32_e32 v166, 16, v107
	v_and_b32_e32 v167, 0xffff0000, v107
	v_pk_mul_f32 v[164:165], v[164:165], v[134:135]
	v_pk_mul_f32 v[166:167], v[166:167], v[142:143]
	v_pk_add_f32 v[164:165], v[164:165], v[162:163]
	v_pk_add_f32 v[164:165], v[164:165], v[166:167]
	v_cvt_pk_bf16_f32 v171, v164, v165
	global_store_dwordx4 v108, v[168:171], s[98:99] offset:2560
	ds_read_b128 v[128:131], v125
	ds_read_b128 v[132:135], v125 offset:16
	ds_read_b128 v[136:139], v125 offset:20480
	ds_read_b128 v[140:143], v125 offset:20496
	s_waitcnt vmcnt(3)
	s_waitcnt lgkmcnt(0)
	v_lshlrev_b32_e32 v144, 16, v112
	v_and_b32_e32 v145, 0xffff0000, v112
	v_lshlrev_b32_e32 v146, 16, v116
	v_and_b32_e32 v147, 0xffff0000, v116
	v_lshlrev_b32_e32 v148, 16, v120
	v_and_b32_e32 v149, 0xffff0000, v120
	v_pk_mul_f32 v[146:147], v[146:147], v[128:129]
	v_pk_mul_f32 v[148:149], v[148:149], v[136:137]
	v_pk_add_f32 v[146:147], v[146:147], v[144:145]
	v_pk_add_f32 v[146:147], v[146:147], v[148:149]
	v_cvt_pk_bf16_f32 v172, v146, v147
	v_lshlrev_b32_e32 v150, 16, v113
	v_and_b32_e32 v151, 0xffff0000, v113
	v_lshlrev_b32_e32 v152, 16, v117
	v_and_b32_e32 v153, 0xffff0000, v117
	v_lshlrev_b32_e32 v154, 16, v121
	v_and_b32_e32 v155, 0xffff0000, v121
	v_pk_mul_f32 v[152:153], v[152:153], v[130:131]
	v_pk_mul_f32 v[154:155], v[154:155], v[138:139]
	v_pk_add_f32 v[152:153], v[152:153], v[150:151]
	v_pk_add_f32 v[152:153], v[152:153], v[154:155]
	v_cvt_pk_bf16_f32 v173, v152, v153
	v_lshlrev_b32_e32 v156, 16, v114
	v_and_b32_e32 v157, 0xffff0000, v114
	v_lshlrev_b32_e32 v158, 16, v118
	v_and_b32_e32 v159, 0xffff0000, v118
	v_lshlrev_b32_e32 v160, 16, v122
	v_and_b32_e32 v161, 0xffff0000, v122
	v_pk_mul_f32 v[158:159], v[158:159], v[132:133]
	v_pk_mul_f32 v[160:161], v[160:161], v[140:141]
	v_pk_add_f32 v[158:159], v[158:159], v[156:157]
	v_pk_add_f32 v[158:159], v[158:159], v[160:161]
	v_cvt_pk_bf16_f32 v174, v158, v159
	v_lshlrev_b32_e32 v162, 16, v115
	v_and_b32_e32 v163, 0xffff0000, v115
	v_lshlrev_b32_e32 v164, 16, v119
	v_and_b32_e32 v165, 0xffff0000, v119
	v_lshlrev_b32_e32 v166, 16, v123
	v_and_b32_e32 v167, 0xffff0000, v123
	v_pk_mul_f32 v[164:165], v[164:165], v[134:135]
	v_pk_mul_f32 v[166:167], v[166:167], v[142:143]
	v_pk_add_f32 v[164:165], v[164:165], v[162:163]
	v_pk_add_f32 v[164:165], v[164:165], v[166:167]
	v_cvt_pk_bf16_f32 v175, v164, v165
	global_store_dwordx4 v124, v[172:175], s[98:99] offset:2560
	s_add_i32 s22, s22, s38
	s_add_i32 s62, s62, 1
	s_add_i32 s61, s61, s52
	s_cmpk_gt_i32 s22, 0xff
	s_cbranch_scc0 .LBB0_500
